# attention QK: K fragments of tile kt+1 read before the MFMAs of tile kt (MFMA/LDS interleave)
# baseline (speedup 1.0000x reference)
.Lau_entry:
	v_and_b32_e32 v3, 63, v0
	v_lshrrev_b32_e32 v4, 6, v0
	v_readfirstlane_b32 s75, v138
	v_and_b32_e32 v1, 15, v3
	v_readfirstlane_b32 s76, v4
	v_lshrrev_b32_e32 v2, 4, v3
	s_lshl_b32 s76, s76, 11
	s_add_i32 s76, s76, 0x24000
	v_lshl_add_u32 v4, v2, 2, v138
	ds_read2_b32 v[10:11], v4 offset0:0 offset1:4
	ds_read2_b32 v[12:13], v4 offset0:8 offset1:12
	ds_read2_b32 v[14:15], v4 offset0:16 offset1:20
	ds_read2_b32 v[16:17], v4 offset0:24 offset1:28
	ds_read2_b32 v[18:19], v4 offset0:32 offset1:36
	ds_read2_b32 v[20:21], v4 offset0:40 offset1:44
	ds_read2_b32 v[22:23], v4 offset0:48 offset1:52
	ds_read2_b32 v[24:25], v4 offset0:56 offset1:60
	ds_read2_b32 v[26:27], v4 offset0:64 offset1:68
	ds_read2_b32 v[28:29], v4 offset0:72 offset1:76
	ds_read2_b32 v[30:31], v4 offset0:80 offset1:84
	ds_read2_b32 v[32:33], v4 offset0:88 offset1:92
	ds_read2_b32 v[34:35], v4 offset0:96 offset1:100
	ds_read2_b32 v[36:37], v4 offset0:104 offset1:108
	ds_read2_b32 v[38:39], v4 offset0:112 offset1:116
	ds_read2_b32 v[40:41], v4 offset0:120 offset1:124
	ds_read2_b32 v[42:43], v4 offset0:128 offset1:132
	ds_read2_b32 v[44:45], v4 offset0:136 offset1:140
	ds_read2_b32 v[46:47], v4 offset0:144 offset1:148
	ds_read2_b32 v[48:49], v4 offset0:152 offset1:156
	ds_read2_b32 v[50:51], v4 offset0:160 offset1:164
	ds_read2_b32 v[52:53], v4 offset0:168 offset1:172
	ds_read2_b32 v[54:55], v4 offset0:176 offset1:180
	ds_read2_b32 v[56:57], v4 offset0:184 offset1:188
	ds_read2_b32 v[58:59], v4 offset0:192 offset1:196
	ds_read2_b32 v[60:61], v4 offset0:200 offset1:204
	ds_read2_b32 v[62:63], v4 offset0:208 offset1:212
	ds_read2_b32 v[64:65], v4 offset0:216 offset1:220
	ds_read2_b32 v[66:67], v4 offset0:224 offset1:228
	ds_read2_b32 v[68:69], v4 offset0:232 offset1:236
	ds_read2_b32 v[70:71], v4 offset0:240 offset1:244
	ds_read2_b32 v[72:73], v4 offset0:248 offset1:252
	v_readlane_b32 s40, v251, 27
	v_readlane_b32 s41, v251, 28
	v_readlane_b32 s42, v251, 29
	v_readlane_b32 s43, v251, 30
	v_readlane_b32 s44, v251, 31
	v_readlane_b32 s45, v251, 32
	v_readlane_b32 s46, v251, 49
	v_readlane_b32 s47, v251, 50
	s_lshl_b32 s8, s70, 11
	s_lshl_b32 s9, s72, 9
	s_add_u32 s56, s40, s8
	s_addc_u32 s57, s41, 0
	s_add_u32 s50, s42, s9
	s_addc_u32 s51, s43, 0
	s_add_u32 s52, s44, s9
	s_addc_u32 s53, s45, 0
	s_add_u32 s58, s46, s8
	s_addc_u32 s59, s47, 0
	v_lshlrev_b32_e32 v5, 1, v2
	v_xor_b32_e32 v5, v1, v5
	v_lshlrev_b32_e32 v5, 4, v5
	v_xor_b32_e32 v6, 0x80, v5
	v_and_b32_e32 v7, 3, v1
	v_and_b32_e32 v8, 8, v1
	v_lshl_or_b32 v8, v7, 1, v8
	v_or_b32_e32 v9, 0, v2
	v_xor_b32_e32 v9, v9, v8
	v_lshlrev_b32_e32 v9, 4, v9
	v_lshl_add_u32 v9, v1, 8, v9
	v_add_u32_e32 v74, s75, v9
	v_or_b32_e32 v9, 4, v2
	v_xor_b32_e32 v9, v9, v8
	v_lshlrev_b32_e32 v9, 4, v9
	v_lshl_add_u32 v9, v1, 8, v9
	v_add_u32_e32 v75, s75, v9
	v_or_b32_e32 v9, 8, v2
	v_xor_b32_e32 v9, v9, v8
	v_lshlrev_b32_e32 v9, 4, v9
	v_lshl_add_u32 v9, v1, 8, v9
	v_add_u32_e32 v76, s75, v9
	v_or_b32_e32 v9, 12, v2
	v_xor_b32_e32 v9, v9, v8
	v_lshlrev_b32_e32 v9, 4, v9
	v_lshl_add_u32 v9, v1, 8, v9
	v_add_u32_e32 v77, s75, v9
	v_lshrrev_b32_e32 v128, 2, v1
	v_lshl_or_b32 v129, v2, 3, v128
	v_and_b32_e32 v130, 1, v2
	v_lshl_or_b32 v130, v130, 2, v128
	v_lshlrev_b32_e32 v129, 8, v129
	v_lshl_add_u32 v129, v7, 3, v129
	v_add_u32_e32 v129, s75, v129
	v_xor_b32_e32 v9, 0, v130
	v_lshl_add_u32 v78, v9, 5, v129
	v_xor_b32_e32 v9, 1, v130
	v_lshl_add_u32 v79, v9, 5, v129
	v_xor_b32_e32 v9, 2, v130
	v_lshl_add_u32 v80, v9, 5, v129
	v_xor_b32_e32 v9, 3, v130
	v_lshl_add_u32 v81, v9, 5, v129
	v_xor_b32_e32 v9, 4, v130
	v_lshl_add_u32 v82, v9, 5, v129
	v_xor_b32_e32 v9, 5, v130
	v_lshl_add_u32 v83, v9, 5, v129
	v_xor_b32_e32 v9, 6, v130
	v_lshl_add_u32 v84, v9, 5, v129
	v_xor_b32_e32 v9, 7, v130
	v_lshl_add_u32 v85, v9, 5, v129
	v_lshl_add_u32 v86, v1, 4, s75
	v_lshl_add_u32 v87, v3, 4, s75
	v_lshl_add_u32 v88, v3, 1, s76
	v_cmp_gt_u32_e64 s[20:21], 4, v1
	v_lshlrev_b32_e32 v9, 4, v2
	v_lshl_add_u32 v128, v7, 9, v9
	v_add_u32_e32 v128, s76, v128
	v_add_u32_e32 v131, 0x22000, v9
	v_cndmask_b32_e64 v89, v131, v128, s[20:21]
	v_lshrrev_b32_e32 v128, 3, v1
	v_add_u32_e32 v128, v128, v1
	v_lshl_add_u32 v132, v128, 4, s75
	v_add_u32_e32 v132, 0x400, v132
	v_and_b32_e32 v128, 3, v3
	v_lshrrev_b32_e32 v129, 2, v3
	v_mul_u32_u24_e32 v131, 0x90, v129
	v_lshl_add_u32 v131, v128, 2, v131
	v_add_u32_e32 v133, s75, v131
	v_add_u32_e32 v133, 0x400, v133
	v_lshlrev_b32_e32 v129, 4, v129
	v_lshl_add_u32 v90, v128, 8, v129
	v_lshl_add_u32 v91, v7, 8, v9
	v_mov_b32_e32 v128, 0
	v_mov_b32_e32 v129, 0
	v_lshlrev_b32_e32 v9, 3, v3
	v_add_u32_e32 v9, 0x22000, v9
	ds_write_b64 v9, v[128:129]
	v_cmp_gt_u32_e64 s[24:25], s73, v3
	v_add_u32_e32 v9, 64, v3
	v_cmp_gt_u32_e64 s[26:27], s73, v9
	v_add_u32_e32 v9, 0x80, v3
	v_cmp_gt_u32_e64 s[28:29], s73, v9
	v_add_u32_e32 v9, 0xc0, v3
	v_cmp_gt_u32_e64 s[30:31], s73, v9
	s_waitcnt lgkmcnt(0)
	v_lshl_add_u32 v10, v10, 9, v5
	v_lshl_add_u32 v11, v11, 9, v5
	v_lshl_add_u32 v12, v12, 9, v6
	v_lshl_add_u32 v13, v13, 9, v6
	v_lshl_add_u32 v14, v14, 9, v5
	v_lshl_add_u32 v15, v15, 9, v5
	v_lshl_add_u32 v16, v16, 9, v6
	v_lshl_add_u32 v17, v17, 9, v6
	v_lshl_add_u32 v18, v18, 9, v5
	v_lshl_add_u32 v19, v19, 9, v5
	v_lshl_add_u32 v20, v20, 9, v6
	v_lshl_add_u32 v21, v21, 9, v6
	v_lshl_add_u32 v22, v22, 9, v5
	v_lshl_add_u32 v23, v23, 9, v5
	v_lshl_add_u32 v24, v24, 9, v6
	v_lshl_add_u32 v25, v25, 9, v6
	v_lshl_add_u32 v26, v26, 9, v5
	v_lshl_add_u32 v27, v27, 9, v5
	v_lshl_add_u32 v28, v28, 9, v6
	v_lshl_add_u32 v29, v29, 9, v6
	v_lshl_add_u32 v30, v30, 9, v5
	v_lshl_add_u32 v31, v31, 9, v5
	v_lshl_add_u32 v32, v32, 9, v6
	v_lshl_add_u32 v33, v33, 9, v6
	v_lshl_add_u32 v34, v34, 9, v5
	v_lshl_add_u32 v35, v35, 9, v5
	v_lshl_add_u32 v36, v36, 9, v6
	v_lshl_add_u32 v37, v37, 9, v6
	v_lshl_add_u32 v38, v38, 9, v5
	v_lshl_add_u32 v39, v39, 9, v5
	v_lshl_add_u32 v40, v40, 9, v6
	v_lshl_add_u32 v41, v41, 9, v6
	v_lshl_add_u32 v42, v42, 9, v5
	v_lshl_add_u32 v43, v43, 9, v5
	v_lshl_add_u32 v44, v44, 9, v6
	v_lshl_add_u32 v45, v45, 9, v6
	v_lshl_add_u32 v46, v46, 9, v5
	v_lshl_add_u32 v47, v47, 9, v5
	v_lshl_add_u32 v48, v48, 9, v6
	v_lshl_add_u32 v49, v49, 9, v6
	v_lshl_add_u32 v50, v50, 9, v5
	v_lshl_add_u32 v51, v51, 9, v5
	v_lshl_add_u32 v52, v52, 9, v6
	v_lshl_add_u32 v53, v53, 9, v6
	v_lshl_add_u32 v54, v54, 9, v5
	v_lshl_add_u32 v55, v55, 9, v5
	v_lshl_add_u32 v56, v56, 9, v6
	v_lshl_add_u32 v57, v57, 9, v6
	v_lshl_add_u32 v58, v58, 9, v5
	v_lshl_add_u32 v59, v59, 9, v5
	v_lshl_add_u32 v60, v60, 9, v6
	v_lshl_add_u32 v61, v61, 9, v6
	v_lshl_add_u32 v62, v62, 9, v5
	v_lshl_add_u32 v63, v63, 9, v5
	v_lshl_add_u32 v64, v64, 9, v6
	v_lshl_add_u32 v65, v65, 9, v6
	v_lshl_add_u32 v66, v66, 9, v5
	v_lshl_add_u32 v67, v67, 9, v5
	v_lshl_add_u32 v68, v68, 9, v6
	v_lshl_add_u32 v69, v69, 9, v6
	v_lshl_add_u32 v70, v70, 9, v5
	v_lshl_add_u32 v71, v71, 9, v5
	v_lshl_add_u32 v72, v72, 9, v6
	v_lshl_add_u32 v73, v73, 9, v6
	s_add_u32 s0, s50, 0
	s_addc_u32 s1, s51, 0
	s_add_u32 s2, s52, 0
	s_addc_u32 s3, s53, 0
	s_add_u32 s4, s56, 0
	s_addc_u32 s5, s57, 0
	s_add_u32 s6, s58, 0
	s_addc_u32 s7, s59, 0
	global_load_dwordx4 v[92:95], v91, s[4:5] offset:0
	global_load_dwordx4 v[96:99], v91, s[4:5] offset:64
	global_load_dwordx4 v[100:103], v91, s[4:5] offset:128
	global_load_dwordx4 v[104:107], v91, s[4:5] offset:192
	s_add_i32 m0, s75, 0x2400
	s_nop 0
	global_load_lds_dwordx4 v10, s[0:1]
	s_add_i32 m0, s75, 0x2800
	s_nop 0
	global_load_lds_dwordx4 v11, s[0:1]
	s_add_i32 m0, s75, 0x2c00
	s_nop 0
	global_load_lds_dwordx4 v12, s[0:1]
	s_add_i32 m0, s75, 0x3000
	s_nop 0
	global_load_lds_dwordx4 v13, s[0:1]
	s_add_i32 m0, s75, 0x3400
	s_nop 0
	global_load_lds_dwordx4 v14, s[0:1]
	s_add_i32 m0, s75, 0x3800
	s_nop 0
	global_load_lds_dwordx4 v15, s[0:1]
	s_add_i32 m0, s75, 0x3c00
	s_nop 0
	global_load_lds_dwordx4 v16, s[0:1]
	s_add_i32 m0, s75, 0x4000
	s_nop 0
	global_load_lds_dwordx4 v17, s[0:1]
	s_add_i32 m0, s75, 0x1400
	s_nop 0
	global_load_lds_dwordx4 v18, s[0:1]
	s_add_i32 m0, s75, 0x1800
	s_nop 0
	global_load_lds_dwordx4 v19, s[0:1]
	s_add_i32 m0, s75, 0x1c00
	s_nop 0
	global_load_lds_dwordx4 v20, s[0:1]
	s_add_i32 m0, s75, 0x2000
	s_nop 0
	global_load_lds_dwordx4 v21, s[0:1]
	s_add_i32 m0, s75, 0x400
	s_nop 0
	global_load_lds_dwordx4 v22, s[0:1]
	s_add_i32 m0, s75, 0x800
	s_nop 0
	global_load_lds_dwordx4 v23, s[0:1]
	s_add_i32 m0, s75, 0xc00
	s_nop 0
	global_load_lds_dwordx4 v24, s[0:1]
	s_add_i32 m0, s75, 0x1000
	s_nop 0
	global_load_lds_dwordx4 v25, s[0:1]
	s_waitcnt vmcnt(12)
	ds_read_b128 v[108:111], v74 offset:9216
	ds_read_b128 v[112:115], v75 offset:9216
	ds_read_b128 v[116:119], v76 offset:9216
	ds_read_b128 v[120:123], v77 offset:9216
	v_cndmask_b32_e64 v92, 0, v92, s[20:21]
	v_cndmask_b32_e64 v93, 0, v93, s[20:21]
	v_cndmask_b32_e64 v94, 0, v94, s[20:21]
	v_cndmask_b32_e64 v95, 0, v95, s[20:21]
	v_cndmask_b32_e64 v96, 0, v96, s[20:21]
	v_cndmask_b32_e64 v97, 0, v97, s[20:21]
	v_cndmask_b32_e64 v98, 0, v98, s[20:21]
	v_cndmask_b32_e64 v99, 0, v99, s[20:21]
	v_cndmask_b32_e64 v100, 0, v100, s[20:21]
	v_cndmask_b32_e64 v101, 0, v101, s[20:21]
	v_cndmask_b32_e64 v102, 0, v102, s[20:21]
	v_cndmask_b32_e64 v103, 0, v103, s[20:21]
	v_cndmask_b32_e64 v104, 0, v104, s[20:21]
	v_cndmask_b32_e64 v105, 0, v105, s[20:21]
	v_cndmask_b32_e64 v106, 0, v106, s[20:21]
	v_cndmask_b32_e64 v107, 0, v107, s[20:21]
	s_waitcnt vmcnt(8)
	ds_read_b128 v[216:219], v74 offset:13312
	ds_read_b128 v[220:223], v75 offset:13312
	ds_read_b128 v[172:175], v76 offset:13312
	ds_read_b128 v[128:131], v77 offset:13312
	s_waitcnt lgkmcnt(4)
	v_mfma_f32_16x16x32_bf16 v[140:143], v[92:95], v[108:111], 0
	s_add_i32 m0, s75, 0x2400
	v_mfma_f32_16x16x32_bf16 v[140:143], v[96:99], v[112:115], v[140:143]
	global_load_lds_dwordx4 v26, s[0:1]
	s_add_i32 m0, s75, 0x2800
	v_mfma_f32_16x16x32_bf16 v[140:143], v[100:103], v[116:119], v[140:143]
	global_load_lds_dwordx4 v27, s[0:1]
	s_add_i32 m0, s75, 0x2c00
	v_mfma_f32_16x16x32_bf16 v[140:143], v[104:107], v[120:123], v[140:143]
	global_load_lds_dwordx4 v28, s[0:1]
	s_add_i32 m0, s75, 0x3000
	s_nop 0
	global_load_lds_dwordx4 v29, s[0:1]
	s_waitcnt vmcnt(8)
	ds_read_b128 v[108:111], v74 offset:5120
	ds_read_b128 v[112:115], v75 offset:5120
	ds_read_b128 v[116:119], v76 offset:5120
	ds_read_b128 v[120:123], v77 offset:5120
	s_waitcnt lgkmcnt(4)
	v_mfma_f32_16x16x32_bf16 v[144:147], v[92:95], v[216:219], 0
	s_add_i32 m0, s75, 0x3400
	v_mfma_f32_16x16x32_bf16 v[144:147], v[96:99], v[220:223], v[144:147]
	global_load_lds_dwordx4 v30, s[0:1]
	s_add_i32 m0, s75, 0x3800
	v_mfma_f32_16x16x32_bf16 v[144:147], v[100:103], v[172:175], v[144:147]
	global_load_lds_dwordx4 v31, s[0:1]
	s_add_i32 m0, s75, 0x3c00
	v_mfma_f32_16x16x32_bf16 v[144:147], v[104:107], v[128:131], v[144:147]
	global_load_lds_dwordx4 v32, s[0:1]
	s_add_i32 m0, s75, 0x4000
	s_nop 0
	global_load_lds_dwordx4 v33, s[0:1]
	s_waitcnt vmcnt(8)
	ds_read_b128 v[216:219], v74 offset:1024
	ds_read_b128 v[220:223], v75 offset:1024
	ds_read_b128 v[172:175], v76 offset:1024
	ds_read_b128 v[128:131], v77 offset:1024
	s_waitcnt lgkmcnt(4)
	v_mfma_f32_16x16x32_bf16 v[148:151], v[92:95], v[108:111], 0
	s_add_i32 m0, s75, 0x1400
	v_mfma_f32_16x16x32_bf16 v[148:151], v[96:99], v[112:115], v[148:151]
	global_load_lds_dwordx4 v34, s[0:1]
	s_add_i32 m0, s75, 0x1800
	v_mfma_f32_16x16x32_bf16 v[148:151], v[100:103], v[116:119], v[148:151]
	global_load_lds_dwordx4 v35, s[0:1]
	s_add_i32 m0, s75, 0x1c00
	v_mfma_f32_16x16x32_bf16 v[148:151], v[104:107], v[120:123], v[148:151]
	global_load_lds_dwordx4 v36, s[0:1]
	s_add_i32 m0, s75, 0x2000
	s_nop 0
	global_load_lds_dwordx4 v37, s[0:1]
	s_waitcnt vmcnt(8)
	ds_read_b128 v[108:111], v74 offset:9216
	ds_read_b128 v[112:115], v75 offset:9216
	ds_read_b128 v[116:119], v76 offset:9216
	ds_read_b128 v[120:123], v77 offset:9216
	s_waitcnt lgkmcnt(4)
	v_mfma_f32_16x16x32_bf16 v[152:155], v[92:95], v[216:219], 0
	s_add_i32 m0, s75, 0x400
	v_mfma_f32_16x16x32_bf16 v[152:155], v[96:99], v[220:223], v[152:155]
	global_load_lds_dwordx4 v38, s[0:1]
	s_add_i32 m0, s75, 0x800
	v_mfma_f32_16x16x32_bf16 v[152:155], v[100:103], v[172:175], v[152:155]
	global_load_lds_dwordx4 v39, s[0:1]
	s_add_i32 m0, s75, 0xc00
	v_mfma_f32_16x16x32_bf16 v[152:155], v[104:107], v[128:131], v[152:155]
	global_load_lds_dwordx4 v40, s[0:1]
	s_add_i32 m0, s75, 0x1000
	s_nop 0
	global_load_lds_dwordx4 v41, s[0:1]
	s_waitcnt vmcnt(8)
	ds_read_b128 v[216:219], v74 offset:13312
	ds_read_b128 v[220:223], v75 offset:13312
	ds_read_b128 v[172:175], v76 offset:13312
	ds_read_b128 v[128:131], v77 offset:13312
	s_waitcnt lgkmcnt(4)
	v_mfma_f32_16x16x32_bf16 v[156:159], v[92:95], v[108:111], 0
	s_add_i32 m0, s75, 0x2400
	v_mfma_f32_16x16x32_bf16 v[156:159], v[96:99], v[112:115], v[156:159]
	global_load_lds_dwordx4 v42, s[0:1]
	s_add_i32 m0, s75, 0x2800
	v_mfma_f32_16x16x32_bf16 v[156:159], v[100:103], v[116:119], v[156:159]
	global_load_lds_dwordx4 v43, s[0:1]
	s_add_i32 m0, s75, 0x2c00
	v_mfma_f32_16x16x32_bf16 v[156:159], v[104:107], v[120:123], v[156:159]
	global_load_lds_dwordx4 v44, s[0:1]
	s_add_i32 m0, s75, 0x3000
	s_nop 0
	global_load_lds_dwordx4 v45, s[0:1]
	s_waitcnt vmcnt(8)
	ds_read_b128 v[108:111], v74 offset:5120
	ds_read_b128 v[112:115], v75 offset:5120
	ds_read_b128 v[116:119], v76 offset:5120
	ds_read_b128 v[120:123], v77 offset:5120
	s_waitcnt lgkmcnt(4)
	v_mfma_f32_16x16x32_bf16 v[160:163], v[92:95], v[216:219], 0
	s_add_i32 m0, s75, 0x3400
	v_mfma_f32_16x16x32_bf16 v[160:163], v[96:99], v[220:223], v[160:163]
	global_load_lds_dwordx4 v46, s[0:1]
	s_add_i32 m0, s75, 0x3800
	v_mfma_f32_16x16x32_bf16 v[160:163], v[100:103], v[172:175], v[160:163]
	global_load_lds_dwordx4 v47, s[0:1]
	s_add_i32 m0, s75, 0x3c00
	v_mfma_f32_16x16x32_bf16 v[160:163], v[104:107], v[128:131], v[160:163]
	global_load_lds_dwordx4 v48, s[0:1]
	s_add_i32 m0, s75, 0x4000
	s_nop 0
	global_load_lds_dwordx4 v49, s[0:1]
	s_waitcnt vmcnt(8)
	ds_read_b128 v[216:219], v74 offset:1024
	ds_read_b128 v[220:223], v75 offset:1024
	ds_read_b128 v[172:175], v76 offset:1024
	ds_read_b128 v[128:131], v77 offset:1024
	s_waitcnt lgkmcnt(4)
	v_mfma_f32_16x16x32_bf16 v[164:167], v[92:95], v[108:111], 0
	s_add_i32 m0, s75, 0x1400
	v_mfma_f32_16x16x32_bf16 v[164:167], v[96:99], v[112:115], v[164:167]
	global_load_lds_dwordx4 v50, s[0:1]
	s_add_i32 m0, s75, 0x1800
	v_mfma_f32_16x16x32_bf16 v[164:167], v[100:103], v[116:119], v[164:167]
	global_load_lds_dwordx4 v51, s[0:1]
	s_add_i32 m0, s75, 0x1c00
	v_mfma_f32_16x16x32_bf16 v[164:167], v[104:107], v[120:123], v[164:167]
	global_load_lds_dwordx4 v52, s[0:1]
	s_add_i32 m0, s75, 0x2000
	s_nop 0
	global_load_lds_dwordx4 v53, s[0:1]
	s_waitcnt vmcnt(8)
	ds_read_b128 v[108:111], v74 offset:9216
	ds_read_b128 v[112:115], v75 offset:9216
	ds_read_b128 v[116:119], v76 offset:9216
	ds_read_b128 v[120:123], v77 offset:9216
	s_waitcnt lgkmcnt(4)
	v_mfma_f32_16x16x32_bf16 v[168:171], v[92:95], v[216:219], 0
	s_add_i32 m0, s75, 0x400
	v_mfma_f32_16x16x32_bf16 v[168:171], v[96:99], v[220:223], v[168:171]
	global_load_lds_dwordx4 v54, s[0:1]
	s_add_i32 m0, s75, 0x800
	v_mfma_f32_16x16x32_bf16 v[168:171], v[100:103], v[172:175], v[168:171]
	global_load_lds_dwordx4 v55, s[0:1]
	s_add_i32 m0, s75, 0xc00
	v_mfma_f32_16x16x32_bf16 v[168:171], v[104:107], v[128:131], v[168:171]
	global_load_lds_dwordx4 v56, s[0:1]
	s_add_i32 m0, s75, 0x1000
	s_nop 0
	global_load_lds_dwordx4 v57, s[0:1]
	s_waitcnt vmcnt(8)
	ds_read_b128 v[216:219], v74 offset:13312
	ds_read_b128 v[220:223], v75 offset:13312
	ds_read_b128 v[172:175], v76 offset:13312
	ds_read_b128 v[128:131], v77 offset:13312
	s_waitcnt lgkmcnt(4)
	v_mfma_f32_16x16x32_bf16 v[184:187], v[92:95], v[108:111], 0
	s_add_i32 m0, s75, 0x2400
	v_mfma_f32_16x16x32_bf16 v[184:187], v[96:99], v[112:115], v[184:187]
	global_load_lds_dwordx4 v58, s[0:1]
	s_add_i32 m0, s75, 0x2800
	v_mfma_f32_16x16x32_bf16 v[184:187], v[100:103], v[116:119], v[184:187]
	global_load_lds_dwordx4 v59, s[0:1]
	s_add_i32 m0, s75, 0x2c00
	v_mfma_f32_16x16x32_bf16 v[184:187], v[104:107], v[120:123], v[184:187]
	global_load_lds_dwordx4 v60, s[0:1]
	s_add_i32 m0, s75, 0x3000
	s_nop 0
	global_load_lds_dwordx4 v61, s[0:1]
	s_waitcnt vmcnt(8)
	ds_read_b128 v[108:111], v74 offset:5120
	ds_read_b128 v[112:115], v75 offset:5120
	ds_read_b128 v[116:119], v76 offset:5120
	ds_read_b128 v[120:123], v77 offset:5120
	s_waitcnt lgkmcnt(4)
	v_mfma_f32_16x16x32_bf16 v[188:191], v[92:95], v[216:219], 0
	s_add_i32 m0, s75, 0x3400
	v_mfma_f32_16x16x32_bf16 v[188:191], v[96:99], v[220:223], v[188:191]
	global_load_lds_dwordx4 v62, s[0:1]
	s_add_i32 m0, s75, 0x3800
	v_mfma_f32_16x16x32_bf16 v[188:191], v[100:103], v[172:175], v[188:191]
	global_load_lds_dwordx4 v63, s[0:1]
	s_add_i32 m0, s75, 0x3c00
	v_mfma_f32_16x16x32_bf16 v[188:191], v[104:107], v[128:131], v[188:191]
	global_load_lds_dwordx4 v64, s[0:1]
	s_add_i32 m0, s75, 0x4000
	s_nop 0
	global_load_lds_dwordx4 v65, s[0:1]
	s_waitcnt vmcnt(8)
	ds_read_b128 v[216:219], v74 offset:1024
	ds_read_b128 v[220:223], v75 offset:1024
	ds_read_b128 v[172:175], v76 offset:1024
	ds_read_b128 v[128:131], v77 offset:1024
	s_waitcnt lgkmcnt(4)
	v_mfma_f32_16x16x32_bf16 v[192:195], v[92:95], v[108:111], 0
	s_add_i32 m0, s75, 0x1400
	v_mfma_f32_16x16x32_bf16 v[192:195], v[96:99], v[112:115], v[192:195]
	global_load_lds_dwordx4 v66, s[0:1]
	s_add_i32 m0, s75, 0x1800
	v_mfma_f32_16x16x32_bf16 v[192:195], v[100:103], v[116:119], v[192:195]
	global_load_lds_dwordx4 v67, s[0:1]
	s_add_i32 m0, s75, 0x1c00
	v_mfma_f32_16x16x32_bf16 v[192:195], v[104:107], v[120:123], v[192:195]
	global_load_lds_dwordx4 v68, s[0:1]
	s_add_i32 m0, s75, 0x2000
	s_nop 0
	global_load_lds_dwordx4 v69, s[0:1]
	s_waitcnt vmcnt(8)
	ds_read_b128 v[108:111], v74 offset:9216
	ds_read_b128 v[112:115], v75 offset:9216
	ds_read_b128 v[116:119], v76 offset:9216
	ds_read_b128 v[120:123], v77 offset:9216
	s_waitcnt lgkmcnt(4)
	v_mfma_f32_16x16x32_bf16 v[196:199], v[92:95], v[216:219], 0
	s_add_i32 m0, s75, 0x400
	v_mfma_f32_16x16x32_bf16 v[196:199], v[96:99], v[220:223], v[196:199]
	global_load_lds_dwordx4 v70, s[0:1]
	s_add_i32 m0, s75, 0x800
	v_mfma_f32_16x16x32_bf16 v[196:199], v[100:103], v[172:175], v[196:199]
	global_load_lds_dwordx4 v71, s[0:1]
	s_add_i32 m0, s75, 0xc00
	v_mfma_f32_16x16x32_bf16 v[196:199], v[104:107], v[128:131], v[196:199]
	global_load_lds_dwordx4 v72, s[0:1]
	s_add_i32 m0, s75, 0x1000
	s_nop 0
	global_load_lds_dwordx4 v73, s[0:1]
	s_waitcnt vmcnt(8)
	ds_read_b128 v[216:219], v74 offset:13312
	ds_read_b128 v[220:223], v75 offset:13312
	ds_read_b128 v[172:175], v76 offset:13312
	ds_read_b128 v[128:131], v77 offset:13312
	s_waitcnt lgkmcnt(4)
	v_mfma_f32_16x16x32_bf16 v[200:203], v[92:95], v[108:111], 0
	v_mfma_f32_16x16x32_bf16 v[200:203], v[96:99], v[112:115], v[200:203]
	v_mfma_f32_16x16x32_bf16 v[200:203], v[100:103], v[116:119], v[200:203]
	v_mfma_f32_16x16x32_bf16 v[200:203], v[104:107], v[120:123], v[200:203]
	s_waitcnt vmcnt(4)
	ds_read_b128 v[108:111], v74 offset:5120
	ds_read_b128 v[112:115], v75 offset:5120
	ds_read_b128 v[116:119], v76 offset:5120
	ds_read_b128 v[120:123], v77 offset:5120
	s_waitcnt lgkmcnt(4)
	v_mfma_f32_16x16x32_bf16 v[204:207], v[92:95], v[216:219], 0
	v_mfma_f32_16x16x32_bf16 v[204:207], v[96:99], v[220:223], v[204:207]
	v_mfma_f32_16x16x32_bf16 v[204:207], v[100:103], v[172:175], v[204:207]
	v_mfma_f32_16x16x32_bf16 v[204:207], v[104:107], v[128:131], v[204:207]
	s_waitcnt vmcnt(0)
	ds_read_b128 v[216:219], v74 offset:1024
	ds_read_b128 v[220:223], v75 offset:1024
	ds_read_b128 v[172:175], v76 offset:1024
	ds_read_b128 v[128:131], v77 offset:1024
	s_waitcnt lgkmcnt(4)
	v_mfma_f32_16x16x32_bf16 v[208:211], v[92:95], v[108:111], 0
	v_mfma_f32_16x16x32_bf16 v[208:211], v[96:99], v[112:115], v[208:211]
	v_mfma_f32_16x16x32_bf16 v[208:211], v[100:103], v[116:119], v[208:211]
	v_mfma_f32_16x16x32_bf16 v[208:211], v[104:107], v[120:123], v[208:211]
	s_waitcnt lgkmcnt(0)
	v_mfma_f32_16x16x32_bf16 v[212:215], v[92:95], v[216:219], 0
	v_mfma_f32_16x16x32_bf16 v[212:215], v[96:99], v[220:223], v[212:215]
	v_mfma_f32_16x16x32_bf16 v[212:215], v[100:103], v[172:175], v[212:215]
	v_mfma_f32_16x16x32_bf16 v[212:215], v[104:107], v[128:131], v[212:215]
	s_nop 7
	s_mov_b64 exec, 0xffff
	ds_write_b128 v86, v[140:143] offset:1024
	ds_write_b128 v86, v[144:147] offset:1280
	ds_write_b128 v86, v[148:151] offset:1536
	ds_write_b128 v86, v[152:155] offset:1792
	ds_write_b128 v86, v[156:159] offset:2048
	ds_write_b128 v86, v[160:163] offset:2304
	ds_write_b128 v86, v[164:167] offset:2560
	ds_write_b128 v86, v[168:171] offset:2816
	ds_write_b128 v86, v[184:187] offset:3072
	ds_write_b128 v86, v[188:191] offset:3328
	ds_write_b128 v86, v[192:195] offset:3584
	ds_write_b128 v86, v[196:199] offset:3840
	ds_write_b128 v86, v[200:203] offset:4096
	ds_write_b128 v86, v[204:207] offset:4352
	ds_write_b128 v86, v[208:211] offset:4608
	ds_write_b128 v86, v[212:215] offset:4864
	s_mov_b64 exec, -1
	s_add_i32 m0, s75, 0x2400
	s_nop 0
	global_load_lds_dwordx4 v10, s[2:3]
	s_add_i32 m0, s75, 0x2800
	s_nop 0
	global_load_lds_dwordx4 v11, s[2:3]
	s_add_i32 m0, s75, 0x2c00
	s_nop 0
	global_load_lds_dwordx4 v12, s[2:3]
	s_add_i32 m0, s75, 0x3000
	s_nop 0
	global_load_lds_dwordx4 v13, s[2:3]
	s_add_i32 m0, s75, 0x3400
	s_nop 0
	global_load_lds_dwordx4 v14, s[2:3]
	s_add_i32 m0, s75, 0x3800
	s_nop 0
	global_load_lds_dwordx4 v15, s[2:3]
	s_add_i32 m0, s75, 0x3c00
	s_nop 0
	global_load_lds_dwordx4 v16, s[2:3]
	s_add_i32 m0, s75, 0x4000
	s_nop 0
	global_load_lds_dwordx4 v17, s[2:3]
	s_waitcnt lgkmcnt(0)
	ds_read_b128 v[108:111], v87 offset:1024
	ds_read_b128 v[112:115], v87 offset:2048
	ds_read_b128 v[116:119], v87 offset:3072
	ds_read_b128 v[120:123], v87 offset:4096
	s_waitcnt lgkmcnt(0)
	s_add_i32 m0, s75, 0x400
	s_nop 0
	global_load_lds_dwordx4 v18, s[2:3]
	s_add_i32 m0, s75, 0x800
	s_nop 0
	global_load_lds_dwordx4 v19, s[2:3]
	s_add_i32 m0, s75, 0xc00
	s_nop 0
	global_load_lds_dwordx4 v20, s[2:3]
	s_add_i32 m0, s75, 0x1000
	s_nop 0
	global_load_lds_dwordx4 v21, s[2:3]
	s_add_i32 m0, s75, 0x1400
	s_nop 0
	global_load_lds_dwordx4 v22, s[2:3]
	s_add_i32 m0, s75, 0x1800
	s_nop 0
	global_load_lds_dwordx4 v23, s[2:3]
	s_add_i32 m0, s75, 0x1c00
	s_nop 0
	global_load_lds_dwordx4 v24, s[2:3]
	s_add_i32 m0, s75, 0x2000
	s_nop 0
	global_load_lds_dwordx4 v25, s[2:3]
	s_cmp_eq_u32 s73, 0x100
	s_cbranch_scc1 .Lau_nomask1_0
	v_mov_b32_e32 v9, 0xff61b1e6
	v_cndmask_b32_e64 v108, v9, v108, s[24:25]
	v_cndmask_b32_e64 v109, v9, v109, s[24:25]
	v_cndmask_b32_e64 v110, v9, v110, s[24:25]
	v_cndmask_b32_e64 v111, v9, v111, s[24:25]
	v_cndmask_b32_e64 v112, v9, v112, s[26:27]
	v_cndmask_b32_e64 v113, v9, v113, s[26:27]
	v_cndmask_b32_e64 v114, v9, v114, s[26:27]
	v_cndmask_b32_e64 v115, v9, v115, s[26:27]
	v_cndmask_b32_e64 v116, v9, v116, s[28:29]
	v_cndmask_b32_e64 v117, v9, v117, s[28:29]
	v_cndmask_b32_e64 v118, v9, v118, s[28:29]
	v_cndmask_b32_e64 v119, v9, v119, s[28:29]
	v_cndmask_b32_e64 v120, v9, v120, s[30:31]
	v_cndmask_b32_e64 v121, v9, v121, s[30:31]
	v_cndmask_b32_e64 v122, v9, v122, s[30:31]
	v_cndmask_b32_e64 v123, v9, v123, s[30:31]

.Lau_nomask2_0:
	s_nop 0
	v_add_f32_e32 v216, 0, v108
	v_add_f32_e32 v217, 0, v109
	v_add_f32_e32 v218, 0, v110
	v_add_f32_e32 v219, 0, v111
	v_add_f32_e32 v216, v112, v216
	v_add_f32_e32 v217, v113, v217
	v_add_f32_e32 v218, v114, v218
	v_add_f32_e32 v219, v115, v219
	v_add_f32_e32 v216, v116, v216
	v_add_f32_e32 v217, v117, v217
	v_add_f32_e32 v218, v118, v218
	v_add_f32_e32 v219, v119, v219
	v_add_f32_e32 v216, v120, v216
	v_add_f32_e32 v217, v121, v217
	v_add_f32_e32 v218, v122, v218
	v_add_f32_e32 v219, v123, v219
	v_add_f32_dpp v216, v216, v216 quad_perm:[1,0,3,2] row_mask:0xf bank_mask:0xf bound_ctrl:1
	v_add_f32_dpp v217, v217, v217 quad_perm:[1,0,3,2] row_mask:0xf bank_mask:0xf bound_ctrl:1
	v_add_f32_dpp v218, v218, v218 quad_perm:[1,0,3,2] row_mask:0xf bank_mask:0xf bound_ctrl:1
	v_add_f32_dpp v219, v219, v219 quad_perm:[1,0,3,2] row_mask:0xf bank_mask:0xf bound_ctrl:1
	v_add_f32_dpp v216, v216, v216 quad_perm:[2,3,0,1] row_mask:0xf bank_mask:0xf bound_ctrl:1
	v_add_f32_dpp v217, v217, v217 quad_perm:[2,3,0,1] row_mask:0xf bank_mask:0xf bound_ctrl:1
	v_add_f32_dpp v218, v218, v218 quad_perm:[2,3,0,1] row_mask:0xf bank_mask:0xf bound_ctrl:1
	v_add_f32_dpp v219, v219, v219 quad_perm:[2,3,0,1] row_mask:0xf bank_mask:0xf bound_ctrl:1
	v_add_f32_dpp v216, v216, v216 row_half_mirror row_mask:0xf bank_mask:0xf bound_ctrl:1
	v_add_f32_dpp v217, v217, v217 row_half_mirror row_mask:0xf bank_mask:0xf bound_ctrl:1
	v_add_f32_dpp v218, v218, v218 row_half_mirror row_mask:0xf bank_mask:0xf bound_ctrl:1
	v_add_f32_dpp v219, v219, v219 row_half_mirror row_mask:0xf bank_mask:0xf bound_ctrl:1
	v_add_f32_dpp v216, v216, v216 row_mirror row_mask:0xf bank_mask:0xf bound_ctrl:1
	v_add_f32_dpp v217, v217, v217 row_mirror row_mask:0xf bank_mask:0xf bound_ctrl:1
	v_add_f32_dpp v218, v218, v218 row_mirror row_mask:0xf bank_mask:0xf bound_ctrl:1
	v_add_f32_dpp v219, v219, v219 row_mirror row_mask:0xf bank_mask:0xf bound_ctrl:1
	v_add_f32_dpp v216, v216, v216 row_bcast:15 row_mask:0xa bank_mask:0xf
	v_add_f32_dpp v217, v217, v217 row_bcast:15 row_mask:0xa bank_mask:0xf
	v_add_f32_dpp v218, v218, v218 row_bcast:15 row_mask:0xa bank_mask:0xf
	v_add_f32_dpp v219, v219, v219 row_bcast:15 row_mask:0xa bank_mask:0xf
	v_add_f32_dpp v216, v216, v216 row_bcast:31 row_mask:0xc bank_mask:0xf
	v_add_f32_dpp v217, v217, v217 row_bcast:31 row_mask:0xc bank_mask:0xf
	v_add_f32_dpp v218, v218, v218 row_bcast:31 row_mask:0xc bank_mask:0xf
	v_add_f32_dpp v219, v219, v219 row_bcast:31 row_mask:0xc bank_mask:0xf
	s_nop 0
	v_readlane_b32 s84, v216, 63
	v_readlane_b32 s85, v217, 63
	v_readlane_b32 s86, v218, 63
	v_readlane_b32 s87, v219, 63
	s_nop 1
	v_mov_b32_e32 v216, s84
	v_mov_b32_e32 v217, s85
	v_mov_b32_e32 v218, s86
	v_mov_b32_e32 v219, s87
	v_div_scale_f32 v220, s[8:9], v216, v216, 1.0
	v_div_scale_f32 v221, s[8:9], v217, v217, 1.0
	v_div_scale_f32 v222, s[8:9], v218, v218, 1.0
	v_div_scale_f32 v223, s[8:9], v219, v219, 1.0
	v_rcp_f32_e32 v128, v220
	v_rcp_f32_e32 v129, v221
	v_rcp_f32_e32 v130, v222
	v_rcp_f32_e32 v131, v223
	s_nop 0
	v_fma_f32 v124, -v220, v128, 1.0
	v_fma_f32 v125, -v221, v129, 1.0
	v_fma_f32 v126, -v222, v130, 1.0
	v_fma_f32 v127, -v223, v131, 1.0
	v_fmac_f32_e32 v128, v124, v128
	v_fmac_f32_e32 v129, v125, v129
	v_fmac_f32_e32 v130, v126, v130
	v_fmac_f32_e32 v131, v127, v131
	v_div_scale_f32 v224, vcc, 1.0, v216, 1.0
	v_mul_f32_e32 v225, v224, v128
	v_fma_f32 v134, -v220, v225, v224
	v_fmac_f32_e32 v225, v134, v128
	v_fma_f32 v220, -v220, v225, v224
	s_nop 0
	v_div_fmas_f32 v220, v220, v128, v225
	v_div_fixup_f32 v220, v220, v216, 1.0
	v_div_scale_f32 v224, vcc, 1.0, v217, 1.0
	v_mul_f32_e32 v225, v224, v129
	v_fma_f32 v134, -v221, v225, v224
	v_fmac_f32_e32 v225, v134, v129
	v_fma_f32 v221, -v221, v225, v224
	s_nop 0
	v_div_fmas_f32 v221, v221, v129, v225
	v_div_fixup_f32 v221, v221, v217, 1.0
	v_div_scale_f32 v224, vcc, 1.0, v218, 1.0
	v_mul_f32_e32 v225, v224, v130
	v_fma_f32 v134, -v222, v225, v224
	v_fmac_f32_e32 v225, v134, v130
	v_fma_f32 v222, -v222, v225, v224
	s_nop 0
	v_div_fmas_f32 v222, v222, v130, v225
	v_div_fixup_f32 v222, v222, v218, 1.0
	v_div_scale_f32 v224, vcc, 1.0, v219, 1.0
	v_mul_f32_e32 v225, v224, v131
	v_fma_f32 v134, -v223, v225, v224
	v_fmac_f32_e32 v225, v134, v131
	v_fma_f32 v223, -v223, v225, v224
	s_nop 0
	v_div_fmas_f32 v223, v223, v131, v225
	v_div_fixup_f32 v223, v223, v219, 1.0
	v_mul_f32_e32 v108, v108, v220
	v_mul_f32_e32 v109, v109, v221
	v_mul_f32_e32 v110, v110, v222
	v_mul_f32_e32 v111, v111, v223
	v_mul_f32_e32 v112, v112, v220
	v_mul_f32_e32 v113, v113, v221
	v_mul_f32_e32 v114, v114, v222
	v_mul_f32_e32 v115, v115, v223
	v_mul_f32_e32 v116, v116, v220
	v_mul_f32_e32 v117, v117, v221
	v_mul_f32_e32 v118, v118, v222
	v_mul_f32_e32 v119, v119, v223
	v_mul_f32_e32 v120, v120, v220
	v_mul_f32_e32 v121, v121, v221
	v_mul_f32_e32 v122, v122, v222
	v_mul_f32_e32 v123, v123, v223
	v_cvt_pk_bf16_f32 v108, v108, v108
	v_cvt_pk_bf16_f32 v109, v109, v109
	v_cvt_pk_bf16_f32 v110, v110, v110
	v_cvt_pk_bf16_f32 v111, v111, v111
	v_cvt_pk_bf16_f32 v112, v112, v112
	v_cvt_pk_bf16_f32 v113, v113, v113
	v_cvt_pk_bf16_f32 v114, v114, v114
	v_cvt_pk_bf16_f32 v115, v115, v115
	v_cvt_pk_bf16_f32 v116, v116, v116
	v_cvt_pk_bf16_f32 v117, v117, v117
	v_cvt_pk_bf16_f32 v118, v118, v118
	v_cvt_pk_bf16_f32 v119, v119, v119
	v_cvt_pk_bf16_f32 v120, v120, v120
	v_cvt_pk_bf16_f32 v121, v121, v121
	v_cvt_pk_bf16_f32 v122, v122, v122
	v_cvt_pk_bf16_f32 v123, v123, v123
	ds_write_b16 v88, v108 offset:0
	ds_write_b16 v88, v109 offset:512
	ds_write_b16 v88, v110 offset:1024
	ds_write_b16 v88, v111 offset:1536
	ds_write_b16 v88, v112 offset:128
	ds_write_b16 v88, v113 offset:640
	ds_write_b16 v88, v114 offset:1152
	ds_write_b16 v88, v115 offset:1664
	ds_write_b16 v88, v116 offset:256
	ds_write_b16 v88, v117 offset:768
	ds_write_b16 v88, v118 offset:1280
	ds_write_b16 v88, v119 offset:1792
	ds_write_b16 v88, v120 offset:384
	ds_write_b16 v88, v121 offset:896
	ds_write_b16 v88, v122 offset:1408
	ds_write_b16 v88, v123 offset:1920
	s_waitcnt vmcnt(8)
	s_waitcnt lgkmcnt(0)
	ds_read_b128 v[172:175], v89 offset:0
	ds_read_b64_tr_b16 v[140:141], v78 offset:9216
	ds_read_b64_tr_b16 v[142:143], v78 offset:10240
	ds_read_b64_tr_b16 v[144:145], v79 offset:9216
	ds_read_b64_tr_b16 v[146:147], v79 offset:10240
	ds_read_b64_tr_b16 v[148:149], v80 offset:9216
	ds_read_b64_tr_b16 v[150:151], v80 offset:10240
	ds_read_b64_tr_b16 v[152:153], v81 offset:9216
	ds_read_b64_tr_b16 v[154:155], v81 offset:10240
	ds_read_b64_tr_b16 v[156:157], v82 offset:9216
	ds_read_b64_tr_b16 v[158:159], v82 offset:10240
	ds_read_b64_tr_b16 v[160:161], v83 offset:9216
	ds_read_b64_tr_b16 v[162:163], v83 offset:10240
	ds_read_b64_tr_b16 v[164:165], v84 offset:9216
	ds_read_b64_tr_b16 v[166:167], v84 offset:10240
	ds_read_b64_tr_b16 v[168:169], v85 offset:9216
	ds_read_b64_tr_b16 v[170:171], v85 offset:10240
	s_waitcnt lgkmcnt(0)
	v_mfma_f32_16x16x32_bf16 v[184:187], v[172:175], v[140:143], 0
	s_add_i32 m0, s75, 0x2400
	v_mfma_f32_16x16x32_bf16 v[188:191], v[172:175], v[144:147], 0
	global_load_lds_dwordx4 v26, s[2:3]
	s_add_i32 m0, s75, 0x2800
	v_mfma_f32_16x16x32_bf16 v[192:195], v[172:175], v[148:151], 0
	global_load_lds_dwordx4 v27, s[2:3]
	s_add_i32 m0, s75, 0x2c00
	v_mfma_f32_16x16x32_bf16 v[196:199], v[172:175], v[152:155], 0
	global_load_lds_dwordx4 v28, s[2:3]
	s_add_i32 m0, s75, 0x3000
	v_mfma_f32_16x16x32_bf16 v[200:203], v[172:175], v[156:159], 0
	global_load_lds_dwordx4 v29, s[2:3]
	s_add_i32 m0, s75, 0x3400
	v_mfma_f32_16x16x32_bf16 v[204:207], v[172:175], v[160:163], 0
	global_load_lds_dwordx4 v30, s[2:3]
	s_add_i32 m0, s75, 0x3800
	v_mfma_f32_16x16x32_bf16 v[208:211], v[172:175], v[164:167], 0
	global_load_lds_dwordx4 v31, s[2:3]
	s_add_i32 m0, s75, 0x3c00
	v_mfma_f32_16x16x32_bf16 v[212:215], v[172:175], v[168:171], 0
	global_load_lds_dwordx4 v32, s[2:3]
	s_add_i32 m0, s75, 0x4000
	s_nop 0
	global_load_lds_dwordx4 v33, s[2:3]
	s_waitcnt vmcnt(8)
	ds_read_b128 v[172:175], v89 offset:64
	ds_read_b64_tr_b16 v[140:141], v78 offset:1024
	ds_read_b64_tr_b16 v[142:143], v78 offset:2048
	ds_read_b64_tr_b16 v[144:145], v79 offset:1024
	ds_read_b64_tr_b16 v[146:147], v79 offset:2048
	ds_read_b64_tr_b16 v[148:149], v80 offset:1024
	ds_read_b64_tr_b16 v[150:151], v80 offset:2048
	ds_read_b64_tr_b16 v[152:153], v81 offset:1024
	ds_read_b64_tr_b16 v[154:155], v81 offset:2048
	ds_read_b64_tr_b16 v[156:157], v82 offset:1024
	ds_read_b64_tr_b16 v[158:159], v82 offset:2048
	ds_read_b64_tr_b16 v[160:161], v83 offset:1024
	ds_read_b64_tr_b16 v[162:163], v83 offset:2048
	ds_read_b64_tr_b16 v[164:165], v84 offset:1024
	ds_read_b64_tr_b16 v[166:167], v84 offset:2048
	ds_read_b64_tr_b16 v[168:169], v85 offset:1024
	ds_read_b64_tr_b16 v[170:171], v85 offset:2048
	s_waitcnt lgkmcnt(0)
	v_mfma_f32_16x16x32_bf16 v[184:187], v[172:175], v[140:143], v[184:187]
	s_add_i32 m0, s75, 0x400
	v_mfma_f32_16x16x32_bf16 v[188:191], v[172:175], v[144:147], v[188:191]
	global_load_lds_dwordx4 v34, s[2:3]
	s_add_i32 m0, s75, 0x800
	v_mfma_f32_16x16x32_bf16 v[192:195], v[172:175], v[148:151], v[192:195]
	global_load_lds_dwordx4 v35, s[2:3]
	s_add_i32 m0, s75, 0xc00
	v_mfma_f32_16x16x32_bf16 v[196:199], v[172:175], v[152:155], v[196:199]
	global_load_lds_dwordx4 v36, s[2:3]
	s_add_i32 m0, s75, 0x1000
	v_mfma_f32_16x16x32_bf16 v[200:203], v[172:175], v[156:159], v[200:203]
	global_load_lds_dwordx4 v37, s[2:3]
	s_add_i32 m0, s75, 0x1400
	v_mfma_f32_16x16x32_bf16 v[204:207], v[172:175], v[160:163], v[204:207]
	global_load_lds_dwordx4 v38, s[2:3]
	s_add_i32 m0, s75, 0x1800
	v_mfma_f32_16x16x32_bf16 v[208:211], v[172:175], v[164:167], v[208:211]
	global_load_lds_dwordx4 v39, s[2:3]
	s_add_i32 m0, s75, 0x1c00
	v_mfma_f32_16x16x32_bf16 v[212:215], v[172:175], v[168:171], v[212:215]
	global_load_lds_dwordx4 v40, s[2:3]
	s_add_i32 m0, s75, 0x2000
	s_nop 0
	global_load_lds_dwordx4 v41, s[2:3]
	s_waitcnt vmcnt(8)
	ds_read_b128 v[172:175], v89 offset:128
	ds_read_b64_tr_b16 v[140:141], v78 offset:9216
	ds_read_b64_tr_b16 v[142:143], v78 offset:10240
	ds_read_b64_tr_b16 v[144:145], v79 offset:9216
	ds_read_b64_tr_b16 v[146:147], v79 offset:10240
	ds_read_b64_tr_b16 v[148:149], v80 offset:9216
	ds_read_b64_tr_b16 v[150:151], v80 offset:10240
	ds_read_b64_tr_b16 v[152:153], v81 offset:9216
	ds_read_b64_tr_b16 v[154:155], v81 offset:10240
	ds_read_b64_tr_b16 v[156:157], v82 offset:9216
	ds_read_b64_tr_b16 v[158:159], v82 offset:10240
	ds_read_b64_tr_b16 v[160:161], v83 offset:9216
	ds_read_b64_tr_b16 v[162:163], v83 offset:10240
	ds_read_b64_tr_b16 v[164:165], v84 offset:9216
	ds_read_b64_tr_b16 v[166:167], v84 offset:10240
	ds_read_b64_tr_b16 v[168:169], v85 offset:9216
	ds_read_b64_tr_b16 v[170:171], v85 offset:10240
	s_waitcnt lgkmcnt(0)
	v_mfma_f32_16x16x32_bf16 v[184:187], v[172:175], v[140:143], v[184:187]
	s_add_i32 m0, s75, 0x2400
	v_mfma_f32_16x16x32_bf16 v[188:191], v[172:175], v[144:147], v[188:191]
	global_load_lds_dwordx4 v42, s[2:3]
	s_add_i32 m0, s75, 0x2800
	v_mfma_f32_16x16x32_bf16 v[192:195], v[172:175], v[148:151], v[192:195]
	global_load_lds_dwordx4 v43, s[2:3]
	s_add_i32 m0, s75, 0x2c00
	v_mfma_f32_16x16x32_bf16 v[196:199], v[172:175], v[152:155], v[196:199]
	global_load_lds_dwordx4 v44, s[2:3]
	s_add_i32 m0, s75, 0x3000
	v_mfma_f32_16x16x32_bf16 v[200:203], v[172:175], v[156:159], v[200:203]
	global_load_lds_dwordx4 v45, s[2:3]
	s_add_i32 m0, s75, 0x3400
	v_mfma_f32_16x16x32_bf16 v[204:207], v[172:175], v[160:163], v[204:207]
	global_load_lds_dwordx4 v46, s[2:3]
	s_add_i32 m0, s75, 0x3800
	v_mfma_f32_16x16x32_bf16 v[208:211], v[172:175], v[164:167], v[208:211]
	global_load_lds_dwordx4 v47, s[2:3]
	s_add_i32 m0, s75, 0x3c00
	v_mfma_f32_16x16x32_bf16 v[212:215], v[172:175], v[168:171], v[212:215]
	global_load_lds_dwordx4 v48, s[2:3]
	s_add_i32 m0, s75, 0x4000
	s_nop 0
	global_load_lds_dwordx4 v49, s[2:3]
	s_waitcnt vmcnt(8)
	ds_read_b128 v[172:175], v89 offset:192
	ds_read_b64_tr_b16 v[140:141], v78 offset:1024
	ds_read_b64_tr_b16 v[142:143], v78 offset:2048
	ds_read_b64_tr_b16 v[144:145], v79 offset:1024
	ds_read_b64_tr_b16 v[146:147], v79 offset:2048
	ds_read_b64_tr_b16 v[148:149], v80 offset:1024
	ds_read_b64_tr_b16 v[150:151], v80 offset:2048
	ds_read_b64_tr_b16 v[152:153], v81 offset:1024
	ds_read_b64_tr_b16 v[154:155], v81 offset:2048
	ds_read_b64_tr_b16 v[156:157], v82 offset:1024
	ds_read_b64_tr_b16 v[158:159], v82 offset:2048
	ds_read_b64_tr_b16 v[160:161], v83 offset:1024
	ds_read_b64_tr_b16 v[162:163], v83 offset:2048
	ds_read_b64_tr_b16 v[164:165], v84 offset:1024
	ds_read_b64_tr_b16 v[166:167], v84 offset:2048
	ds_read_b64_tr_b16 v[168:169], v85 offset:1024
	ds_read_b64_tr_b16 v[170:171], v85 offset:2048
	s_waitcnt lgkmcnt(0)
	v_mfma_f32_16x16x32_bf16 v[184:187], v[172:175], v[140:143], v[184:187]
	s_add_i32 m0, s75, 0x400
	v_mfma_f32_16x16x32_bf16 v[188:191], v[172:175], v[144:147], v[188:191]
	global_load_lds_dwordx4 v50, s[2:3]
	s_add_i32 m0, s75, 0x800
	v_mfma_f32_16x16x32_bf16 v[192:195], v[172:175], v[148:151], v[192:195]
	global_load_lds_dwordx4 v51, s[2:3]
	s_add_i32 m0, s75, 0xc00
	v_mfma_f32_16x16x32_bf16 v[196:199], v[172:175], v[152:155], v[196:199]
	global_load_lds_dwordx4 v52, s[2:3]
	s_add_i32 m0, s75, 0x1000
	v_mfma_f32_16x16x32_bf16 v[200:203], v[172:175], v[156:159], v[200:203]
	global_load_lds_dwordx4 v53, s[2:3]
	s_add_i32 m0, s75, 0x1400
	v_mfma_f32_16x16x32_bf16 v[204:207], v[172:175], v[160:163], v[204:207]
	global_load_lds_dwordx4 v54, s[2:3]
	s_add_i32 m0, s75, 0x1800
	v_mfma_f32_16x16x32_bf16 v[208:211], v[172:175], v[164:167], v[208:211]
	global_load_lds_dwordx4 v55, s[2:3]
	s_add_i32 m0, s75, 0x1c00
	v_mfma_f32_16x16x32_bf16 v[212:215], v[172:175], v[168:171], v[212:215]
	global_load_lds_dwordx4 v56, s[2:3]
	s_add_i32 m0, s75, 0x2000
	s_nop 0
	global_load_lds_dwordx4 v57, s[2:3]
	s_waitcnt vmcnt(8)
	ds_read_b128 v[172:175], v89 offset:256
	ds_read_b64_tr_b16 v[140:141], v78 offset:9216
	ds_read_b64_tr_b16 v[142:143], v78 offset:10240
	ds_read_b64_tr_b16 v[144:145], v79 offset:9216
	ds_read_b64_tr_b16 v[146:147], v79 offset:10240
	ds_read_b64_tr_b16 v[148:149], v80 offset:9216
	ds_read_b64_tr_b16 v[150:151], v80 offset:10240
	ds_read_b64_tr_b16 v[152:153], v81 offset:9216
	ds_read_b64_tr_b16 v[154:155], v81 offset:10240
	ds_read_b64_tr_b16 v[156:157], v82 offset:9216
	ds_read_b64_tr_b16 v[158:159], v82 offset:10240
	ds_read_b64_tr_b16 v[160:161], v83 offset:9216
	ds_read_b64_tr_b16 v[162:163], v83 offset:10240
	ds_read_b64_tr_b16 v[164:165], v84 offset:9216
	ds_read_b64_tr_b16 v[166:167], v84 offset:10240
	ds_read_b64_tr_b16 v[168:169], v85 offset:9216
	ds_read_b64_tr_b16 v[170:171], v85 offset:10240
	s_waitcnt lgkmcnt(0)
	v_mfma_f32_16x16x32_bf16 v[184:187], v[172:175], v[140:143], v[184:187]
	s_add_i32 m0, s75, 0x2400
	v_mfma_f32_16x16x32_bf16 v[188:191], v[172:175], v[144:147], v[188:191]
	global_load_lds_dwordx4 v58, s[2:3]
	s_add_i32 m0, s75, 0x2800
	v_mfma_f32_16x16x32_bf16 v[192:195], v[172:175], v[148:151], v[192:195]
	global_load_lds_dwordx4 v59, s[2:3]
	s_add_i32 m0, s75, 0x2c00
	v_mfma_f32_16x16x32_bf16 v[196:199], v[172:175], v[152:155], v[196:199]
	global_load_lds_dwordx4 v60, s[2:3]
	s_add_i32 m0, s75, 0x3000
	v_mfma_f32_16x16x32_bf16 v[200:203], v[172:175], v[156:159], v[200:203]
	global_load_lds_dwordx4 v61, s[2:3]
	s_add_i32 m0, s75, 0x3400
	v_mfma_f32_16x16x32_bf16 v[204:207], v[172:175], v[160:163], v[204:207]
	global_load_lds_dwordx4 v62, s[2:3]
	s_add_i32 m0, s75, 0x3800
	v_mfma_f32_16x16x32_bf16 v[208:211], v[172:175], v[164:167], v[208:211]
	global_load_lds_dwordx4 v63, s[2:3]
	s_add_i32 m0, s75, 0x3c00
	v_mfma_f32_16x16x32_bf16 v[212:215], v[172:175], v[168:171], v[212:215]
	global_load_lds_dwordx4 v64, s[2:3]
	s_add_i32 m0, s75, 0x4000
	s_nop 0
	global_load_lds_dwordx4 v65, s[2:3]
	s_waitcnt vmcnt(8)
	ds_read_b128 v[172:175], v89 offset:320
	ds_read_b64_tr_b16 v[140:141], v78 offset:1024
	ds_read_b64_tr_b16 v[142:143], v78 offset:2048
	ds_read_b64_tr_b16 v[144:145], v79 offset:1024
	ds_read_b64_tr_b16 v[146:147], v79 offset:2048
	ds_read_b64_tr_b16 v[148:149], v80 offset:1024
	ds_read_b64_tr_b16 v[150:151], v80 offset:2048
	ds_read_b64_tr_b16 v[152:153], v81 offset:1024
	ds_read_b64_tr_b16 v[154:155], v81 offset:2048
	ds_read_b64_tr_b16 v[156:157], v82 offset:1024
	ds_read_b64_tr_b16 v[158:159], v82 offset:2048
	ds_read_b64_tr_b16 v[160:161], v83 offset:1024
	ds_read_b64_tr_b16 v[162:163], v83 offset:2048
	ds_read_b64_tr_b16 v[164:165], v84 offset:1024
	ds_read_b64_tr_b16 v[166:167], v84 offset:2048
	ds_read_b64_tr_b16 v[168:169], v85 offset:1024
	ds_read_b64_tr_b16 v[170:171], v85 offset:2048
	s_waitcnt lgkmcnt(0)
	v_mfma_f32_16x16x32_bf16 v[184:187], v[172:175], v[140:143], v[184:187]
	s_add_i32 m0, s75, 0x400
	v_mfma_f32_16x16x32_bf16 v[188:191], v[172:175], v[144:147], v[188:191]
	global_load_lds_dwordx4 v66, s[2:3]
	s_add_i32 m0, s75, 0x800
	v_mfma_f32_16x16x32_bf16 v[192:195], v[172:175], v[148:151], v[192:195]
	global_load_lds_dwordx4 v67, s[2:3]
	s_add_i32 m0, s75, 0xc00
	v_mfma_f32_16x16x32_bf16 v[196:199], v[172:175], v[152:155], v[196:199]
	global_load_lds_dwordx4 v68, s[2:3]
	s_add_i32 m0, s75, 0x1000
	v_mfma_f32_16x16x32_bf16 v[200:203], v[172:175], v[156:159], v[200:203]
	global_load_lds_dwordx4 v69, s[2:3]
	s_add_i32 m0, s75, 0x1400
	v_mfma_f32_16x16x32_bf16 v[204:207], v[172:175], v[160:163], v[204:207]
	global_load_lds_dwordx4 v70, s[2:3]
	s_add_i32 m0, s75, 0x1800
	v_mfma_f32_16x16x32_bf16 v[208:211], v[172:175], v[164:167], v[208:211]
	global_load_lds_dwordx4 v71, s[2:3]
	s_add_i32 m0, s75, 0x1c00
	v_mfma_f32_16x16x32_bf16 v[212:215], v[172:175], v[168:171], v[212:215]
	global_load_lds_dwordx4 v72, s[2:3]
	s_add_i32 m0, s75, 0x2000
	s_nop 0
	global_load_lds_dwordx4 v73, s[2:3]
	s_waitcnt vmcnt(8)
	ds_read_b128 v[172:175], v89 offset:384
	ds_read_b64_tr_b16 v[140:141], v78 offset:9216
	ds_read_b64_tr_b16 v[142:143], v78 offset:10240
	ds_read_b64_tr_b16 v[144:145], v79 offset:9216
	ds_read_b64_tr_b16 v[146:147], v79 offset:10240
	ds_read_b64_tr_b16 v[148:149], v80 offset:9216
	ds_read_b64_tr_b16 v[150:151], v80 offset:10240
	ds_read_b64_tr_b16 v[152:153], v81 offset:9216
	ds_read_b64_tr_b16 v[154:155], v81 offset:10240
	ds_read_b64_tr_b16 v[156:157], v82 offset:9216
	ds_read_b64_tr_b16 v[158:159], v82 offset:10240
	ds_read_b64_tr_b16 v[160:161], v83 offset:9216
	ds_read_b64_tr_b16 v[162:163], v83 offset:10240
	ds_read_b64_tr_b16 v[164:165], v84 offset:9216
	ds_read_b64_tr_b16 v[166:167], v84 offset:10240
	ds_read_b64_tr_b16 v[168:169], v85 offset:9216
	ds_read_b64_tr_b16 v[170:171], v85 offset:10240
	s_waitcnt lgkmcnt(0)
	s_add_u32 s0, s0, 0x100
	s_addc_u32 s1, s1, 0
	s_add_u32 s4, s4, 0x400
	s_addc_u32 s5, s5, 0
	global_load_dwordx4 v[92:95], v91, s[4:5] offset:0
	global_load_dwordx4 v[96:99], v91, s[4:5] offset:64
	global_load_dwordx4 v[100:103], v91, s[4:5] offset:128
	global_load_dwordx4 v[104:107], v91, s[4:5] offset:192
	v_mfma_f32_16x16x32_bf16 v[184:187], v[172:175], v[140:143], v[184:187]
	s_add_i32 m0, s75, 0x2400
	v_mfma_f32_16x16x32_bf16 v[188:191], v[172:175], v[144:147], v[188:191]
	global_load_lds_dwordx4 v10, s[0:1]
	s_add_i32 m0, s75, 0x2800
	v_mfma_f32_16x16x32_bf16 v[192:195], v[172:175], v[148:151], v[192:195]
	global_load_lds_dwordx4 v11, s[0:1]
	s_add_i32 m0, s75, 0x2c00
	v_mfma_f32_16x16x32_bf16 v[196:199], v[172:175], v[152:155], v[196:199]
	global_load_lds_dwordx4 v12, s[0:1]
	s_add_i32 m0, s75, 0x3000
	v_mfma_f32_16x16x32_bf16 v[200:203], v[172:175], v[156:159], v[200:203]
	global_load_lds_dwordx4 v13, s[0:1]
	s_add_i32 m0, s75, 0x3400
	v_mfma_f32_16x16x32_bf16 v[204:207], v[172:175], v[160:163], v[204:207]
	global_load_lds_dwordx4 v14, s[0:1]
	s_add_i32 m0, s75, 0x3800
	v_mfma_f32_16x16x32_bf16 v[208:211], v[172:175], v[164:167], v[208:211]
	global_load_lds_dwordx4 v15, s[0:1]
	s_add_i32 m0, s75, 0x3c00
	v_mfma_f32_16x16x32_bf16 v[212:215], v[172:175], v[168:171], v[212:215]
	global_load_lds_dwordx4 v16, s[0:1]
	s_add_i32 m0, s75, 0x4000
	s_nop 0
	global_load_lds_dwordx4 v17, s[0:1]
	s_waitcnt vmcnt(12)
	ds_read_b128 v[172:175], v89 offset:448
	ds_read_b64_tr_b16 v[140:141], v78 offset:1024
	ds_read_b64_tr_b16 v[142:143], v78 offset:2048
	ds_read_b64_tr_b16 v[144:145], v79 offset:1024
	ds_read_b64_tr_b16 v[146:147], v79 offset:2048
	ds_read_b64_tr_b16 v[148:149], v80 offset:1024
	ds_read_b64_tr_b16 v[150:151], v80 offset:2048
	ds_read_b64_tr_b16 v[152:153], v81 offset:1024
	ds_read_b64_tr_b16 v[154:155], v81 offset:2048
	ds_read_b64_tr_b16 v[156:157], v82 offset:1024
	ds_read_b64_tr_b16 v[158:159], v82 offset:2048
	ds_read_b64_tr_b16 v[160:161], v83 offset:1024
	ds_read_b64_tr_b16 v[162:163], v83 offset:2048
	ds_read_b64_tr_b16 v[164:165], v84 offset:1024
	ds_read_b64_tr_b16 v[166:167], v84 offset:2048
	ds_read_b64_tr_b16 v[168:169], v85 offset:1024
	ds_read_b64_tr_b16 v[170:171], v85 offset:2048
	s_waitcnt lgkmcnt(0)
	v_mfma_f32_16x16x32_bf16 v[184:187], v[172:175], v[140:143], v[184:187]
	s_add_i32 m0, s75, 0x1400
	v_mfma_f32_16x16x32_bf16 v[188:191], v[172:175], v[144:147], v[188:191]
	global_load_lds_dwordx4 v18, s[0:1]
	s_add_i32 m0, s75, 0x1800
	v_mfma_f32_16x16x32_bf16 v[192:195], v[172:175], v[148:151], v[192:195]
	global_load_lds_dwordx4 v19, s[0:1]
	s_add_i32 m0, s75, 0x1c00
	v_mfma_f32_16x16x32_bf16 v[196:199], v[172:175], v[152:155], v[196:199]
	global_load_lds_dwordx4 v20, s[0:1]
	s_add_i32 m0, s75, 0x2000
	v_mfma_f32_16x16x32_bf16 v[200:203], v[172:175], v[156:159], v[200:203]
	global_load_lds_dwordx4 v21, s[0:1]
	v_mfma_f32_16x16x32_bf16 v[204:207], v[172:175], v[160:163], v[204:207]
	v_mfma_f32_16x16x32_bf16 v[208:211], v[172:175], v[164:167], v[208:211]
	v_mfma_f32_16x16x32_bf16 v[212:215], v[172:175], v[168:171], v[212:215]
	s_nop 7
	s_mov_b64 exec, 0xffff
	ds_write_b128 v132, v[184:187] offset:0
	ds_write_b128 v132, v[188:191] offset:288
	ds_write_b128 v132, v[192:195] offset:576
	ds_write_b128 v132, v[196:199] offset:864
	ds_write_b128 v132, v[200:203] offset:1152
	ds_write_b128 v132, v[204:207] offset:1440
	ds_write_b128 v132, v[208:211] offset:1728
	ds_write_b128 v132, v[212:215] offset:2016
	s_mov_b64 exec, -1
	s_waitcnt lgkmcnt(0)
	ds_read_b32 v140, v133 offset:0
	ds_read_b32 v141, v133 offset:16
	ds_read_b32 v142, v133 offset:32
	ds_read_b32 v143, v133 offset:48
	ds_read_b32 v144, v133 offset:64
	ds_read_b32 v145, v133 offset:80
	ds_read_b32 v146, v133 offset:96
	ds_read_b32 v147, v133 offset:112
	s_waitcnt lgkmcnt(0)
	v_cvt_pk_bf16_f32 v148, v140, v141
	v_cvt_pk_bf16_f32 v149, v142, v143
	v_cvt_pk_bf16_f32 v150, v144, v145
	v_cvt_pk_bf16_f32 v151, v146, v147
	global_store_dwordx4 v90, v[148:151], s[6:7]
	s_add_u32 s2, s52, 0x100
	s_addc_u32 s3, s53, 0
	s_add_u32 s6, s58, 0x400
	s_addc_u32 s7, s59, 0
	s_add_i32 m0, s75, 0x400
	s_nop 0
	global_load_lds_dwordx4 v22, s[0:1]
	s_add_i32 m0, s75, 0x800
	s_nop 0
	global_load_lds_dwordx4 v23, s[0:1]
	s_add_i32 m0, s75, 0xc00
	s_nop 0
	global_load_lds_dwordx4 v24, s[0:1]
	s_add_i32 m0, s75, 0x1000
	s_nop 0
	global_load_lds_dwordx4 v25, s[0:1]
	s_waitcnt vmcnt(8)
	ds_read_b128 v[108:111], v74 offset:9216
	ds_read_b128 v[112:115], v75 offset:9216
	ds_read_b128 v[116:119], v76 offset:9216
	ds_read_b128 v[120:123], v77 offset:9216
	v_cndmask_b32_e64 v92, 0, v92, s[20:21]
	v_cndmask_b32_e64 v93, 0, v93, s[20:21]
	v_cndmask_b32_e64 v94, 0, v94, s[20:21]
	v_cndmask_b32_e64 v95, 0, v95, s[20:21]
	v_cndmask_b32_e64 v96, 0, v96, s[20:21]
	v_cndmask_b32_e64 v97, 0, v97, s[20:21]
	v_cndmask_b32_e64 v98, 0, v98, s[20:21]
	v_cndmask_b32_e64 v99, 0, v99, s[20:21]
	v_cndmask_b32_e64 v100, 0, v100, s[20:21]
	v_cndmask_b32_e64 v101, 0, v101, s[20:21]
	v_cndmask_b32_e64 v102, 0, v102, s[20:21]
	v_cndmask_b32_e64 v103, 0, v103, s[20:21]
	v_cndmask_b32_e64 v104, 0, v104, s[20:21]
	v_cndmask_b32_e64 v105, 0, v105, s[20:21]
	v_cndmask_b32_e64 v106, 0, v106, s[20:21]
	v_cndmask_b32_e64 v107, 0, v107, s[20:21]
	s_waitcnt vmcnt(8)
	ds_read_b128 v[216:219], v74 offset:13312
	ds_read_b128 v[220:223], v75 offset:13312
	ds_read_b128 v[172:175], v76 offset:13312
	ds_read_b128 v[128:131], v77 offset:13312
	s_waitcnt lgkmcnt(4)
	v_mfma_f32_16x16x32_bf16 v[140:143], v[92:95], v[108:111], 0
	s_add_i32 m0, s75, 0x2400
	v_mfma_f32_16x16x32_bf16 v[140:143], v[96:99], v[112:115], v[140:143]
	global_load_lds_dwordx4 v26, s[0:1]
	s_add_i32 m0, s75, 0x2800
	v_mfma_f32_16x16x32_bf16 v[140:143], v[100:103], v[116:119], v[140:143]
	global_load_lds_dwordx4 v27, s[0:1]
	s_add_i32 m0, s75, 0x2c00
	v_mfma_f32_16x16x32_bf16 v[140:143], v[104:107], v[120:123], v[140:143]
	global_load_lds_dwordx4 v28, s[0:1]
	s_add_i32 m0, s75, 0x3000
	s_nop 0
	global_load_lds_dwordx4 v29, s[0:1]
	s_waitcnt vmcnt(8)
	ds_read_b128 v[108:111], v74 offset:5120
	ds_read_b128 v[112:115], v75 offset:5120
	ds_read_b128 v[116:119], v76 offset:5120
	ds_read_b128 v[120:123], v77 offset:5120
	s_waitcnt lgkmcnt(4)
	v_mfma_f32_16x16x32_bf16 v[144:147], v[92:95], v[216:219], 0
	s_add_i32 m0, s75, 0x3400
	v_mfma_f32_16x16x32_bf16 v[144:147], v[96:99], v[220:223], v[144:147]
	global_load_lds_dwordx4 v30, s[0:1]
	s_add_i32 m0, s75, 0x3800
	v_mfma_f32_16x16x32_bf16 v[144:147], v[100:103], v[172:175], v[144:147]
	global_load_lds_dwordx4 v31, s[0:1]
	s_add_i32 m0, s75, 0x3c00
	v_mfma_f32_16x16x32_bf16 v[144:147], v[104:107], v[128:131], v[144:147]
	global_load_lds_dwordx4 v32, s[0:1]
	s_add_i32 m0, s75, 0x4000
	s_nop 0
	global_load_lds_dwordx4 v33, s[0:1]
	s_waitcnt vmcnt(8)
	ds_read_b128 v[216:219], v74 offset:1024
	ds_read_b128 v[220:223], v75 offset:1024
	ds_read_b128 v[172:175], v76 offset:1024
	ds_read_b128 v[128:131], v77 offset:1024
	s_waitcnt lgkmcnt(4)
	v_mfma_f32_16x16x32_bf16 v[148:151], v[92:95], v[108:111], 0
	s_add_i32 m0, s75, 0x1400
	v_mfma_f32_16x16x32_bf16 v[148:151], v[96:99], v[112:115], v[148:151]
	global_load_lds_dwordx4 v34, s[0:1]
	s_add_i32 m0, s75, 0x1800
	v_mfma_f32_16x16x32_bf16 v[148:151], v[100:103], v[116:119], v[148:151]
	global_load_lds_dwordx4 v35, s[0:1]
	s_add_i32 m0, s75, 0x1c00
	v_mfma_f32_16x16x32_bf16 v[148:151], v[104:107], v[120:123], v[148:151]
	global_load_lds_dwordx4 v36, s[0:1]
	s_add_i32 m0, s75, 0x2000
	s_nop 0
	global_load_lds_dwordx4 v37, s[0:1]
	s_waitcnt vmcnt(8)
	ds_read_b128 v[108:111], v74 offset:9216
	ds_read_b128 v[112:115], v75 offset:9216
	ds_read_b128 v[116:119], v76 offset:9216
	ds_read_b128 v[120:123], v77 offset:9216
	s_waitcnt lgkmcnt(4)
	v_mfma_f32_16x16x32_bf16 v[152:155], v[92:95], v[216:219], 0
	s_add_i32 m0, s75, 0x400
	v_mfma_f32_16x16x32_bf16 v[152:155], v[96:99], v[220:223], v[152:155]
	global_load_lds_dwordx4 v38, s[0:1]
	s_add_i32 m0, s75, 0x800
	v_mfma_f32_16x16x32_bf16 v[152:155], v[100:103], v[172:175], v[152:155]
	global_load_lds_dwordx4 v39, s[0:1]
	s_add_i32 m0, s75, 0xc00
	v_mfma_f32_16x16x32_bf16 v[152:155], v[104:107], v[128:131], v[152:155]
	global_load_lds_dwordx4 v40, s[0:1]
	s_add_i32 m0, s75, 0x1000
	s_nop 0
	global_load_lds_dwordx4 v41, s[0:1]
	s_waitcnt vmcnt(8)
	ds_read_b128 v[216:219], v74 offset:13312
	ds_read_b128 v[220:223], v75 offset:13312
	ds_read_b128 v[172:175], v76 offset:13312
	ds_read_b128 v[128:131], v77 offset:13312
	s_waitcnt lgkmcnt(4)
	v_mfma_f32_16x16x32_bf16 v[156:159], v[92:95], v[108:111], 0
	s_add_i32 m0, s75, 0x2400
	v_mfma_f32_16x16x32_bf16 v[156:159], v[96:99], v[112:115], v[156:159]
	global_load_lds_dwordx4 v42, s[0:1]
	s_add_i32 m0, s75, 0x2800
	v_mfma_f32_16x16x32_bf16 v[156:159], v[100:103], v[116:119], v[156:159]
	global_load_lds_dwordx4 v43, s[0:1]
	s_add_i32 m0, s75, 0x2c00
	v_mfma_f32_16x16x32_bf16 v[156:159], v[104:107], v[120:123], v[156:159]
	global_load_lds_dwordx4 v44, s[0:1]
	s_add_i32 m0, s75, 0x3000
	s_nop 0
	global_load_lds_dwordx4 v45, s[0:1]
	s_waitcnt vmcnt(8)
	ds_read_b128 v[108:111], v74 offset:5120
	ds_read_b128 v[112:115], v75 offset:5120
	ds_read_b128 v[116:119], v76 offset:5120
	ds_read_b128 v[120:123], v77 offset:5120
	s_waitcnt lgkmcnt(4)
	v_mfma_f32_16x16x32_bf16 v[160:163], v[92:95], v[216:219], 0
	s_add_i32 m0, s75, 0x3400
	v_mfma_f32_16x16x32_bf16 v[160:163], v[96:99], v[220:223], v[160:163]
	global_load_lds_dwordx4 v46, s[0:1]
	s_add_i32 m0, s75, 0x3800
	v_mfma_f32_16x16x32_bf16 v[160:163], v[100:103], v[172:175], v[160:163]
	global_load_lds_dwordx4 v47, s[0:1]
	s_add_i32 m0, s75, 0x3c00
	v_mfma_f32_16x16x32_bf16 v[160:163], v[104:107], v[128:131], v[160:163]
	global_load_lds_dwordx4 v48, s[0:1]
	s_add_i32 m0, s75, 0x4000
	s_nop 0
	global_load_lds_dwordx4 v49, s[0:1]
	s_waitcnt vmcnt(8)
	ds_read_b128 v[216:219], v74 offset:1024
	ds_read_b128 v[220:223], v75 offset:1024
	ds_read_b128 v[172:175], v76 offset:1024
	ds_read_b128 v[128:131], v77 offset:1024
	s_waitcnt lgkmcnt(4)
	v_mfma_f32_16x16x32_bf16 v[164:167], v[92:95], v[108:111], 0
	s_add_i32 m0, s75, 0x1400
	v_mfma_f32_16x16x32_bf16 v[164:167], v[96:99], v[112:115], v[164:167]
	global_load_lds_dwordx4 v50, s[0:1]
	s_add_i32 m0, s75, 0x1800
	v_mfma_f32_16x16x32_bf16 v[164:167], v[100:103], v[116:119], v[164:167]
	global_load_lds_dwordx4 v51, s[0:1]
	s_add_i32 m0, s75, 0x1c00
	v_mfma_f32_16x16x32_bf16 v[164:167], v[104:107], v[120:123], v[164:167]
	global_load_lds_dwordx4 v52, s[0:1]
	s_add_i32 m0, s75, 0x2000
	s_nop 0
	global_load_lds_dwordx4 v53, s[0:1]
	s_waitcnt vmcnt(8)
	ds_read_b128 v[108:111], v74 offset:9216
	ds_read_b128 v[112:115], v75 offset:9216
	ds_read_b128 v[116:119], v76 offset:9216
	ds_read_b128 v[120:123], v77 offset:9216
	s_waitcnt lgkmcnt(4)
	v_mfma_f32_16x16x32_bf16 v[168:171], v[92:95], v[216:219], 0
	s_add_i32 m0, s75, 0x400
	v_mfma_f32_16x16x32_bf16 v[168:171], v[96:99], v[220:223], v[168:171]
	global_load_lds_dwordx4 v54, s[0:1]
	s_add_i32 m0, s75, 0x800
	v_mfma_f32_16x16x32_bf16 v[168:171], v[100:103], v[172:175], v[168:171]
	global_load_lds_dwordx4 v55, s[0:1]
	s_add_i32 m0, s75, 0xc00
	v_mfma_f32_16x16x32_bf16 v[168:171], v[104:107], v[128:131], v[168:171]
	global_load_lds_dwordx4 v56, s[0:1]
	s_add_i32 m0, s75, 0x1000
	s_nop 0
	global_load_lds_dwordx4 v57, s[0:1]
	s_waitcnt vmcnt(8)
	ds_read_b128 v[216:219], v74 offset:13312
	ds_read_b128 v[220:223], v75 offset:13312
	ds_read_b128 v[172:175], v76 offset:13312
	ds_read_b128 v[128:131], v77 offset:13312
	s_waitcnt lgkmcnt(4)
	v_mfma_f32_16x16x32_bf16 v[184:187], v[92:95], v[108:111], 0
	s_add_i32 m0, s75, 0x2400
	v_mfma_f32_16x16x32_bf16 v[184:187], v[96:99], v[112:115], v[184:187]
	global_load_lds_dwordx4 v58, s[0:1]
	s_add_i32 m0, s75, 0x2800
	v_mfma_f32_16x16x32_bf16 v[184:187], v[100:103], v[116:119], v[184:187]
	global_load_lds_dwordx4 v59, s[0:1]
	s_add_i32 m0, s75, 0x2c00
	v_mfma_f32_16x16x32_bf16 v[184:187], v[104:107], v[120:123], v[184:187]
	global_load_lds_dwordx4 v60, s[0:1]
	s_add_i32 m0, s75, 0x3000
	s_nop 0
	global_load_lds_dwordx4 v61, s[0:1]
	s_waitcnt vmcnt(8)
	ds_read_b128 v[108:111], v74 offset:5120
	ds_read_b128 v[112:115], v75 offset:5120
	ds_read_b128 v[116:119], v76 offset:5120
	ds_read_b128 v[120:123], v77 offset:5120
	s_waitcnt lgkmcnt(4)
	v_mfma_f32_16x16x32_bf16 v[188:191], v[92:95], v[216:219], 0
	s_add_i32 m0, s75, 0x3400
	v_mfma_f32_16x16x32_bf16 v[188:191], v[96:99], v[220:223], v[188:191]
	global_load_lds_dwordx4 v62, s[0:1]
	s_add_i32 m0, s75, 0x3800
	v_mfma_f32_16x16x32_bf16 v[188:191], v[100:103], v[172:175], v[188:191]
	global_load_lds_dwordx4 v63, s[0:1]
	s_add_i32 m0, s75, 0x3c00
	v_mfma_f32_16x16x32_bf16 v[188:191], v[104:107], v[128:131], v[188:191]
	global_load_lds_dwordx4 v64, s[0:1]
	s_add_i32 m0, s75, 0x4000
	s_nop 0
	global_load_lds_dwordx4 v65, s[0:1]
	s_waitcnt vmcnt(8)
	ds_read_b128 v[216:219], v74 offset:1024
	ds_read_b128 v[220:223], v75 offset:1024
	ds_read_b128 v[172:175], v76 offset:1024
	ds_read_b128 v[128:131], v77 offset:1024
	s_waitcnt lgkmcnt(4)
	v_mfma_f32_16x16x32_bf16 v[192:195], v[92:95], v[108:111], 0
	s_add_i32 m0, s75, 0x1400
	v_mfma_f32_16x16x32_bf16 v[192:195], v[96:99], v[112:115], v[192:195]
	global_load_lds_dwordx4 v66, s[0:1]
	s_add_i32 m0, s75, 0x1800
	v_mfma_f32_16x16x32_bf16 v[192:195], v[100:103], v[116:119], v[192:195]
	global_load_lds_dwordx4 v67, s[0:1]
	s_add_i32 m0, s75, 0x1c00
	v_mfma_f32_16x16x32_bf16 v[192:195], v[104:107], v[120:123], v[192:195]
	global_load_lds_dwordx4 v68, s[0:1]
	s_add_i32 m0, s75, 0x2000
	s_nop 0
	global_load_lds_dwordx4 v69, s[0:1]
	s_waitcnt vmcnt(8)
	ds_read_b128 v[108:111], v74 offset:9216
	ds_read_b128 v[112:115], v75 offset:9216
	ds_read_b128 v[116:119], v76 offset:9216
	ds_read_b128 v[120:123], v77 offset:9216
	s_waitcnt lgkmcnt(4)
	v_mfma_f32_16x16x32_bf16 v[196:199], v[92:95], v[216:219], 0
	s_add_i32 m0, s75, 0x400
	v_mfma_f32_16x16x32_bf16 v[196:199], v[96:99], v[220:223], v[196:199]
	global_load_lds_dwordx4 v70, s[0:1]
	s_add_i32 m0, s75, 0x800
	v_mfma_f32_16x16x32_bf16 v[196:199], v[100:103], v[172:175], v[196:199]
	global_load_lds_dwordx4 v71, s[0:1]
	s_add_i32 m0, s75, 0xc00
	v_mfma_f32_16x16x32_bf16 v[196:199], v[104:107], v[128:131], v[196:199]
	global_load_lds_dwordx4 v72, s[0:1]
	s_add_i32 m0, s75, 0x1000
	s_nop 0
	global_load_lds_dwordx4 v73, s[0:1]
	s_waitcnt vmcnt(8)
	ds_read_b128 v[216:219], v74 offset:13312
	ds_read_b128 v[220:223], v75 offset:13312
	ds_read_b128 v[172:175], v76 offset:13312
	ds_read_b128 v[128:131], v77 offset:13312
	s_waitcnt lgkmcnt(4)
	v_mfma_f32_16x16x32_bf16 v[200:203], v[92:95], v[108:111], 0
	v_mfma_f32_16x16x32_bf16 v[200:203], v[96:99], v[112:115], v[200:203]
	v_mfma_f32_16x16x32_bf16 v[200:203], v[100:103], v[116:119], v[200:203]
	v_mfma_f32_16x16x32_bf16 v[200:203], v[104:107], v[120:123], v[200:203]
	s_waitcnt vmcnt(4)
	ds_read_b128 v[108:111], v74 offset:5120
	ds_read_b128 v[112:115], v75 offset:5120
	ds_read_b128 v[116:119], v76 offset:5120
	ds_read_b128 v[120:123], v77 offset:5120
	s_waitcnt lgkmcnt(4)
	v_mfma_f32_16x16x32_bf16 v[204:207], v[92:95], v[216:219], 0
	v_mfma_f32_16x16x32_bf16 v[204:207], v[96:99], v[220:223], v[204:207]
	v_mfma_f32_16x16x32_bf16 v[204:207], v[100:103], v[172:175], v[204:207]
	v_mfma_f32_16x16x32_bf16 v[204:207], v[104:107], v[128:131], v[204:207]
	s_waitcnt vmcnt(0)
	ds_read_b128 v[216:219], v74 offset:1024
	ds_read_b128 v[220:223], v75 offset:1024
	ds_read_b128 v[172:175], v76 offset:1024
	ds_read_b128 v[128:131], v77 offset:1024
	s_waitcnt lgkmcnt(4)
	v_mfma_f32_16x16x32_bf16 v[208:211], v[92:95], v[108:111], 0
	v_mfma_f32_16x16x32_bf16 v[208:211], v[96:99], v[112:115], v[208:211]
	v_mfma_f32_16x16x32_bf16 v[208:211], v[100:103], v[116:119], v[208:211]
	v_mfma_f32_16x16x32_bf16 v[208:211], v[104:107], v[120:123], v[208:211]
	s_waitcnt lgkmcnt(0)
	v_mfma_f32_16x16x32_bf16 v[212:215], v[92:95], v[216:219], 0
	v_mfma_f32_16x16x32_bf16 v[212:215], v[96:99], v[220:223], v[212:215]
	v_mfma_f32_16x16x32_bf16 v[212:215], v[100:103], v[172:175], v[212:215]
	v_mfma_f32_16x16x32_bf16 v[212:215], v[104:107], v[128:131], v[212:215]
	s_nop 7
	s_mov_b64 exec, 0xffff
	ds_write_b128 v86, v[140:143] offset:1024
	ds_write_b128 v86, v[144:147] offset:1280
	ds_write_b128 v86, v[148:151] offset:1536
	ds_write_b128 v86, v[152:155] offset:1792
	ds_write_b128 v86, v[156:159] offset:2048
	ds_write_b128 v86, v[160:163] offset:2304
	ds_write_b128 v86, v[164:167] offset:2560
	ds_write_b128 v86, v[168:171] offset:2816
	ds_write_b128 v86, v[184:187] offset:3072
	ds_write_b128 v86, v[188:191] offset:3328
	ds_write_b128 v86, v[192:195] offset:3584
	ds_write_b128 v86, v[196:199] offset:3840
	ds_write_b128 v86, v[200:203] offset:4096
	ds_write_b128 v86, v[204:207] offset:4352
	ds_write_b128 v86, v[208:211] offset:4608
	ds_write_b128 v86, v[212:215] offset:4864
	s_mov_b64 exec, -1
	s_add_i32 m0, s75, 0x2400
	s_nop 0
	global_load_lds_dwordx4 v10, s[2:3]
	s_add_i32 m0, s75, 0x2800
	s_nop 0
	global_load_lds_dwordx4 v11, s[2:3]
	s_add_i32 m0, s75, 0x2c00
	s_nop 0
	global_load_lds_dwordx4 v12, s[2:3]
	s_add_i32 m0, s75, 0x3000
	s_nop 0
	global_load_lds_dwordx4 v13, s[2:3]
	s_add_i32 m0, s75, 0x3400
	s_nop 0
	global_load_lds_dwordx4 v14, s[2:3]
	s_add_i32 m0, s75, 0x3800
	s_nop 0
	global_load_lds_dwordx4 v15, s[2:3]
	s_add_i32 m0, s75, 0x3c00
	s_nop 0
	global_load_lds_dwordx4 v16, s[2:3]
	s_add_i32 m0, s75, 0x4000
	s_nop 0
	global_load_lds_dwordx4 v17, s[2:3]
	s_waitcnt lgkmcnt(0)
	ds_read_b128 v[108:111], v87 offset:1024
	ds_read_b128 v[112:115], v87 offset:2048
	ds_read_b128 v[116:119], v87 offset:3072
	ds_read_b128 v[120:123], v87 offset:4096
	s_waitcnt lgkmcnt(0)
	s_add_i32 m0, s75, 0x400
	s_nop 0
	global_load_lds_dwordx4 v18, s[2:3]
	s_add_i32 m0, s75, 0x800
	s_nop 0
	global_load_lds_dwordx4 v19, s[2:3]
	s_add_i32 m0, s75, 0xc00
	s_nop 0
	global_load_lds_dwordx4 v20, s[2:3]
	s_add_i32 m0, s75, 0x1000
	s_nop 0
	global_load_lds_dwordx4 v21, s[2:3]
	s_add_i32 m0, s75, 0x1400
	s_nop 0
	global_load_lds_dwordx4 v22, s[2:3]
	s_add_i32 m0, s75, 0x1800
	s_nop 0
	global_load_lds_dwordx4 v23, s[2:3]
	s_add_i32 m0, s75, 0x1c00
	s_nop 0
	global_load_lds_dwordx4 v24, s[2:3]
	s_add_i32 m0, s75, 0x2000
	s_nop 0
	global_load_lds_dwordx4 v25, s[2:3]
	s_cmp_eq_u32 s73, 0x100
	s_cbranch_scc1 .Lau_nomask1_1
	v_mov_b32_e32 v9, 0xff61b1e6
	v_cndmask_b32_e64 v108, v9, v108, s[24:25]
	v_cndmask_b32_e64 v109, v9, v109, s[24:25]
	v_cndmask_b32_e64 v110, v9, v110, s[24:25]
	v_cndmask_b32_e64 v111, v9, v111, s[24:25]
	v_cndmask_b32_e64 v112, v9, v112, s[26:27]
	v_cndmask_b32_e64 v113, v9, v113, s[26:27]
	v_cndmask_b32_e64 v114, v9, v114, s[26:27]
	v_cndmask_b32_e64 v115, v9, v115, s[26:27]
	v_cndmask_b32_e64 v116, v9, v116, s[28:29]
	v_cndmask_b32_e64 v117, v9, v117, s[28:29]
	v_cndmask_b32_e64 v118, v9, v118, s[28:29]
	v_cndmask_b32_e64 v119, v9, v119, s[28:29]
	v_cndmask_b32_e64 v120, v9, v120, s[30:31]
	v_cndmask_b32_e64 v121, v9, v121, s[30:31]
	v_cndmask_b32_e64 v122, v9, v122, s[30:31]
	v_cndmask_b32_e64 v123, v9, v123, s[30:31]
